# GEMM rstd epilogues (in-projection x4, up-projection x4): the full vmcnt drain before the next unit's row-sum reduction replaced by the count that covers the row-sum loads (the unit's stores stay in f
# speedup vs baseline: 1.0029x; 1.0029x over previous
.LBB0_705:
	s_waitcnt vmcnt(16)
	v_pk_add_f32 v[10:11], v[14:15], v[10:11]
	v_pk_add_f32 v[8:9], v[12:13], v[8:9]
	v_pk_add_f32 v[0:1], v[4:5], v[0:1]
	v_pk_add_f32 v[2:3], v[6:7], v[2:3]
	v_pk_add_f32 v[0:1], v[8:9], v[0:1]
	v_pk_add_f32 v[2:3], v[10:11], v[2:3]
	v_add_f32_e32 v0, v0, v1
	v_add_f32_e32 v1, v2, v3
	v_add_f32_e32 v0, v0, v1
	ds_bpermute_b32 v1, v202, v0
	s_and_saveexec_b64 s[4:5], s[0:1]
	s_cbranch_execz .LBB0_707
	s_waitcnt lgkmcnt(0)
	v_add_f32_e32 v0, v0, v1
	v_fmamk_f32 v0, v0, 0x3a000000, v216
	v_mul_f32_e32 v1, 0x4b800000, v0
	v_cmp_gt_f32_e32 vcc, s87, v0
	s_lshl_b32 s6, s88, 10
	s_and_b32 s6, s6, 0x400
	v_cndmask_b32_e32 v0, v0, v1, vcc
	v_rsq_f32_e32 v0, v0
	s_nop 0
	v_mul_f32_e32 v1, 0x45800000, v0
	v_cndmask_b32_e32 v0, v0, v1, vcc
	v_add_u32_e32 v1, s6, v205
	ds_write_b32 v1, v0

.LBB0_1782:
	s_ashr_i32 s67, s66, 31
	s_lshl_b64 s[38:39], s[66:67], 15
	v_lshl_add_u64 v[140:141], v[158:159], 0, s[38:39]
	global_load_dwordx4 v[128:131], v[140:141], off offset:32
	global_load_dwordx4 v[132:135], v[140:141], off offset:48
	global_load_dwordx4 v[136:139], v[140:141], off
	s_nop 0
	global_load_dwordx4 v[140:143], v[140:141], off offset:16
	v_lshl_or_b32 v176, s29, 8, v172
	s_lshl_b32 s29, s30, 10
	s_and_b32 s29, s29, 0x400
	v_add_u32_e32 v160, s29, v171
	ds_read2_b32 v[178:179], v160 offset1:16
	ds_read2_b32 v[180:181], v160 offset0:32 offset1:48
	ds_read2_b32 v[162:163], v160 offset0:128 offset1:144
	ds_read2_b32 v[160:161], v160 offset0:160 offset1:176
	v_lshl_add_u32 v174, s60, 8, v168
	s_waitcnt lgkmcnt(0)
	v_pk_mul_f32 v[122:123], v[122:123], v[178:179] op_sel_hi:[1,0]
	v_ashrrev_i32_e32 v175, 31, v174
	v_pk_mul_f32 v[126:127], v[126:127], v[178:179] op_sel_hi:[1,0]
	v_pk_mul_f32 v[124:125], v[124:125], v[178:179] op_sel_hi:[1,0]
	v_pk_mul_f32 v[120:121], v[120:121], v[178:179] op_sel_hi:[1,0]
	v_max_f32_e32 v122, 0, v122
	v_lshlrev_b64 v[182:183], 14, v[174:175]
	v_max_f32_e32 v124, 0, v124
	v_max_f32_e32 v120, 0, v120
	v_max_f32_e32 v121, 0, v121
	v_max_f32_e32 v126, 0, v126
	v_mul_f32_e32 v175, v122, v122
	v_max_f32_e32 v122, 0, v127
	v_ashrrev_i32_e32 v177, 31, v176
	v_mul_f32_e32 v124, v124, v124
	v_mul_f32_e32 v120, v120, v120
	v_max_f32_e32 v125, 0, v125
	v_mul_f32_e32 v121, v121, v121
	v_mul_f32_e32 v126, v126, v126
	v_max_f32_e32 v123, 0, v123
	v_mul_f32_e32 v127, v122, v122
	v_mul_f32_e32 v125, v125, v125
	v_mul_f32_e32 v184, v123, v123
	v_cvt_pk_bf16_f32 v122, v124, v125
	v_cvt_pk_bf16_f32 v123, v126, v127
	v_cvt_pk_bf16_f32 v124, v120, v121
	v_lshl_add_u64 v[120:121], s[26:27], 0, v[182:183]
	v_lshlrev_b64 v[126:127], 1, v[176:177]
	v_pk_mul_f32 v[114:115], v[114:115], v[178:179] op_sel_hi:[1,0]
	v_pk_mul_f32 v[112:113], v[112:113], v[178:179] op_sel_hi:[1,0]
	v_lshl_add_u64 v[120:121], v[120:121], 0, v[126:127]
	v_pk_mul_f32 v[118:119], v[118:119], v[178:179] op_sel_hi:[1,0]
	v_pk_mul_f32 v[116:117], v[116:117], v[178:179] op_sel_hi:[1,0]
	v_max_f32_e32 v112, 0, v112
	v_max_f32_e32 v113, 0, v113
	v_max_f32_e32 v114, 0, v114
	v_cvt_pk_bf16_f32 v125, v175, v184
	global_store_dwordx4 v[120:121], v[122:125], off
	v_max_f32_e32 v116, 0, v116
	v_max_f32_e32 v115, 0, v115
	v_mul_f32_e32 v122, v112, v112
	v_max_f32_e32 v112, 0, v117
	v_mul_f32_e32 v117, v113, v113
	v_max_f32_e32 v113, 0, v118
	v_mul_f32_e32 v118, v114, v114
	v_max_f32_e32 v114, 0, v119
	v_mul_f32_e32 v112, v112, v112
	v_mul_f32_e32 v113, v113, v113
	v_mul_f32_e32 v114, v114, v114
	v_mul_f32_e32 v116, v116, v116
	v_mul_f32_e32 v115, v115, v115
	v_cvt_pk_bf16_f32 v112, v116, v112
	v_cvt_pk_bf16_f32 v113, v113, v114
	v_cvt_pk_bf16_f32 v114, v122, v117
	v_cvt_pk_bf16_f32 v115, v118, v115
	global_store_dwordx4 v[120:121], v[112:115], off offset:256
	v_pk_mul_f32 v[90:91], v[90:91], v[180:181] op_sel_hi:[1,0]
	v_pk_mul_f32 v[88:89], v[88:89], v[180:181] op_sel_hi:[1,0]
	v_mov_b32_e32 v114, v179
	v_pk_mul_f32 v[106:107], v[106:107], v[114:115] op_sel_hi:[1,0]
	v_pk_mul_f32 v[104:105], v[104:105], v[114:115] op_sel_hi:[1,0]
	v_or_b32_e32 v112, 16, v174
	v_pk_mul_f32 v[110:111], v[110:111], v[114:115] op_sel_hi:[1,0]
	v_pk_mul_f32 v[108:109], v[108:109], v[114:115] op_sel_hi:[1,0]
	v_max_f32_e32 v104, 0, v104
	v_max_f32_e32 v105, 0, v105
	v_max_f32_e32 v106, 0, v106
	v_ashrrev_i32_e32 v113, 31, v112
	v_max_f32_e32 v108, 0, v108
	v_mul_f32_e32 v115, v104, v104
	v_max_f32_e32 v104, 0, v109
	v_mul_f32_e32 v109, v105, v105
	v_max_f32_e32 v105, 0, v110
	v_mul_f32_e32 v110, v106, v106
	v_max_f32_e32 v106, 0, v111
	v_lshlrev_b64 v[112:113], 14, v[112:113]
	v_mul_f32_e32 v108, v108, v108
	v_mul_f32_e32 v104, v104, v104
	v_mul_f32_e32 v105, v105, v105
	v_mul_f32_e32 v106, v106, v106
	v_max_f32_e32 v107, 0, v107
	v_cvt_pk_bf16_f32 v104, v108, v104
	v_cvt_pk_bf16_f32 v105, v105, v106
	v_cvt_pk_bf16_f32 v106, v115, v109
	v_lshl_add_u64 v[108:109], s[26:27], 0, v[112:113]
	v_pk_mul_f32 v[96:97], v[96:97], v[114:115] op_sel_hi:[1,0]
	v_mul_f32_e32 v107, v107, v107
	v_lshl_add_u64 v[108:109], v[108:109], 0, v[126:127]
	v_pk_mul_f32 v[100:101], v[100:101], v[114:115] op_sel_hi:[1,0]
	v_pk_mul_f32 v[98:99], v[98:99], v[114:115] op_sel_hi:[1,0]
	v_max_f32_e32 v96, 0, v96
	v_cvt_pk_bf16_f32 v107, v110, v107
	global_store_dwordx4 v[108:109], v[104:107], off
	v_pk_mul_f32 v[102:103], v[102:103], v[114:115] op_sel_hi:[1,0]
	v_max_f32_e32 v97, 0, v97
	v_mul_f32_e32 v104, v96, v96
	v_max_f32_e32 v96, 0, v101
	v_max_f32_e32 v98, 0, v98
	v_max_f32_e32 v100, 0, v100
	v_mul_f32_e32 v96, v96, v96
	v_mul_f32_e32 v101, v97, v97
	v_max_f32_e32 v97, 0, v102
	v_mul_f32_e32 v102, v98, v98
	v_max_f32_e32 v98, 0, v103
	v_max_f32_e32 v99, 0, v99
	v_mul_f32_e32 v100, v100, v100
	v_mul_f32_e32 v97, v97, v97
	v_mul_f32_e32 v98, v98, v98
	v_mul_f32_e32 v99, v99, v99
	v_cvt_pk_bf16_f32 v96, v100, v96
	v_cvt_pk_bf16_f32 v97, v97, v98
	v_cvt_pk_bf16_f32 v98, v104, v101
	v_cvt_pk_bf16_f32 v99, v102, v99
	global_store_dwordx4 v[108:109], v[96:99], off offset:256
	v_pk_mul_f32 v[94:95], v[94:95], v[180:181] op_sel_hi:[1,0]
	v_pk_mul_f32 v[92:93], v[92:93], v[180:181] op_sel_hi:[1,0]
	v_or_b32_e32 v96, 32, v174
	v_max_f32_e32 v88, 0, v88
	v_max_f32_e32 v89, 0, v89
	v_max_f32_e32 v90, 0, v90
	v_ashrrev_i32_e32 v97, 31, v96
	v_max_f32_e32 v92, 0, v92
	v_mul_f32_e32 v98, v88, v88
	v_max_f32_e32 v88, 0, v93
	v_mul_f32_e32 v93, v89, v89
	v_max_f32_e32 v89, 0, v94
	v_mul_f32_e32 v94, v90, v90
	v_max_f32_e32 v90, 0, v95
	v_lshlrev_b64 v[96:97], 14, v[96:97]
	v_mul_f32_e32 v92, v92, v92
	v_mul_f32_e32 v88, v88, v88
	v_mul_f32_e32 v89, v89, v89
	v_mul_f32_e32 v90, v90, v90
	v_max_f32_e32 v91, 0, v91
	v_cvt_pk_bf16_f32 v88, v92, v88
	v_cvt_pk_bf16_f32 v89, v89, v90
	v_cvt_pk_bf16_f32 v90, v98, v93
	v_lshl_add_u64 v[92:93], s[26:27], 0, v[96:97]
	v_pk_mul_f32 v[82:83], v[82:83], v[180:181] op_sel_hi:[1,0]
	v_pk_mul_f32 v[80:81], v[80:81], v[180:181] op_sel_hi:[1,0]
	v_mul_f32_e32 v91, v91, v91
	v_lshl_add_u64 v[92:93], v[92:93], 0, v[126:127]
	v_pk_mul_f32 v[86:87], v[86:87], v[180:181] op_sel_hi:[1,0]
	v_pk_mul_f32 v[84:85], v[84:85], v[180:181] op_sel_hi:[1,0]
	v_max_f32_e32 v80, 0, v80
	v_max_f32_e32 v81, 0, v81
	v_max_f32_e32 v82, 0, v82
	v_cvt_pk_bf16_f32 v91, v94, v91
	global_store_dwordx4 v[92:93], v[88:91], off
	v_max_f32_e32 v84, 0, v84
	v_max_f32_e32 v83, 0, v83
	v_mul_f32_e32 v88, v80, v80
	v_max_f32_e32 v80, 0, v85
	v_mul_f32_e32 v85, v81, v81
	v_max_f32_e32 v81, 0, v86
	v_mul_f32_e32 v86, v82, v82
	v_max_f32_e32 v82, 0, v87
	v_mul_f32_e32 v80, v80, v80
	v_mul_f32_e32 v81, v81, v81
	v_mul_f32_e32 v82, v82, v82
	v_mul_f32_e32 v84, v84, v84
	v_mul_f32_e32 v83, v83, v83
	v_cvt_pk_bf16_f32 v80, v84, v80
	v_cvt_pk_bf16_f32 v81, v81, v82
	v_cvt_pk_bf16_f32 v82, v88, v85
	v_cvt_pk_bf16_f32 v83, v86, v83
	global_store_dwordx4 v[92:93], v[80:83], off offset:256
	v_pk_mul_f32 v[58:59], v[58:59], v[162:163] op_sel_hi:[1,0]
	v_pk_mul_f32 v[56:57], v[56:57], v[162:163] op_sel_hi:[1,0]
	v_mov_b32_e32 v82, v181
	v_pk_mul_f32 v[74:75], v[74:75], v[82:83] op_sel_hi:[1,0]
	v_pk_mul_f32 v[72:73], v[72:73], v[82:83] op_sel_hi:[1,0]
	v_or_b32_e32 v80, 48, v174
	v_pk_mul_f32 v[78:79], v[78:79], v[82:83] op_sel_hi:[1,0]
	v_pk_mul_f32 v[76:77], v[76:77], v[82:83] op_sel_hi:[1,0]
	v_max_f32_e32 v72, 0, v72
	v_max_f32_e32 v73, 0, v73
	v_max_f32_e32 v74, 0, v74
	v_ashrrev_i32_e32 v81, 31, v80
	v_max_f32_e32 v76, 0, v76
	v_mul_f32_e32 v83, v72, v72
	v_max_f32_e32 v72, 0, v77
	v_mul_f32_e32 v77, v73, v73
	v_max_f32_e32 v73, 0, v78
	v_mul_f32_e32 v78, v74, v74
	v_max_f32_e32 v74, 0, v79
	v_lshlrev_b64 v[80:81], 14, v[80:81]
	v_mul_f32_e32 v76, v76, v76
	v_mul_f32_e32 v72, v72, v72
	v_mul_f32_e32 v73, v73, v73
	v_mul_f32_e32 v74, v74, v74
	v_max_f32_e32 v75, 0, v75
	v_cvt_pk_bf16_f32 v72, v76, v72
	v_cvt_pk_bf16_f32 v73, v73, v74
	v_cvt_pk_bf16_f32 v74, v83, v77
	v_lshl_add_u64 v[76:77], s[26:27], 0, v[80:81]
	v_pk_mul_f32 v[64:65], v[64:65], v[82:83] op_sel_hi:[1,0]
	v_mul_f32_e32 v75, v75, v75
	v_lshl_add_u64 v[76:77], v[76:77], 0, v[126:127]
	v_pk_mul_f32 v[68:69], v[68:69], v[82:83] op_sel_hi:[1,0]
	v_pk_mul_f32 v[66:67], v[66:67], v[82:83] op_sel_hi:[1,0]
	v_max_f32_e32 v64, 0, v64
	v_cvt_pk_bf16_f32 v75, v78, v75
	global_store_dwordx4 v[76:77], v[72:75], off
	v_pk_mul_f32 v[70:71], v[70:71], v[82:83] op_sel_hi:[1,0]
	v_max_f32_e32 v65, 0, v65
	v_mul_f32_e32 v72, v64, v64
	v_max_f32_e32 v64, 0, v69
	v_max_f32_e32 v66, 0, v66
	v_max_f32_e32 v68, 0, v68
	v_mul_f32_e32 v64, v64, v64
	v_mul_f32_e32 v69, v65, v65
	v_max_f32_e32 v65, 0, v70
	v_mul_f32_e32 v70, v66, v66
	v_max_f32_e32 v66, 0, v71
	v_max_f32_e32 v67, 0, v67
	v_mul_f32_e32 v68, v68, v68
	v_mul_f32_e32 v65, v65, v65
	v_mul_f32_e32 v66, v66, v66
	v_mul_f32_e32 v67, v67, v67
	v_cvt_pk_bf16_f32 v64, v68, v64
	v_pk_mul_f32 v[62:63], v[62:63], v[162:163] op_sel_hi:[1,0]
	v_pk_mul_f32 v[60:61], v[60:61], v[162:163] op_sel_hi:[1,0]
	v_max_f32_e32 v56, 0, v56
	v_max_f32_e32 v57, 0, v57
	v_max_f32_e32 v58, 0, v58
	v_cvt_pk_bf16_f32 v65, v65, v66
	v_cvt_pk_bf16_f32 v66, v72, v69
	v_cvt_pk_bf16_f32 v67, v70, v67
	global_store_dwordx4 v[76:77], v[64:67], off offset:256
	v_max_f32_e32 v59, 0, v59
	v_max_f32_e32 v60, 0, v60
	v_mul_f32_e32 v64, v56, v56
	v_max_f32_e32 v56, 0, v61
	v_mul_f32_e32 v61, v57, v57
	v_max_f32_e32 v57, 0, v62
	v_mul_f32_e32 v62, v58, v58
	v_max_f32_e32 v58, 0, v63
	v_mul_f32_e32 v56, v56, v56
	v_mul_f32_e32 v57, v57, v57
	v_mul_f32_e32 v58, v58, v58
	v_mul_f32_e32 v59, v59, v59
	s_mov_b32 s29, 0x200000
	v_mul_f32_e32 v60, v60, v60
	v_cvt_pk_bf16_f32 v56, v60, v56
	v_cvt_pk_bf16_f32 v57, v57, v58
	v_cvt_pk_bf16_f32 v58, v64, v61
	v_cvt_pk_bf16_f32 v59, v62, v59
	v_add_co_u32_e32 v62, vcc, s29, v120
	v_pk_mul_f32 v[48:49], v[48:49], v[162:163] op_sel_hi:[1,0]
	s_nop 0
	v_addc_co_u32_e32 v63, vcc, 0, v121, vcc
	v_pk_mul_f32 v[52:53], v[52:53], v[162:163] op_sel_hi:[1,0]
	v_pk_mul_f32 v[50:51], v[50:51], v[162:163] op_sel_hi:[1,0]
	v_max_f32_e32 v48, 0, v48
	global_store_dwordx4 v[62:63], v[56:59], off
	v_pk_mul_f32 v[54:55], v[54:55], v[162:163] op_sel_hi:[1,0]
	v_max_f32_e32 v49, 0, v49
	v_mul_f32_e32 v56, v48, v48
	v_max_f32_e32 v48, 0, v53
	v_max_f32_e32 v50, 0, v50
	s_mov_b64 s[30:31], 0x200000
	v_max_f32_e32 v52, 0, v52
	v_mul_f32_e32 v48, v48, v48
	v_mul_f32_e32 v53, v49, v49
	v_max_f32_e32 v49, 0, v54
	v_mul_f32_e32 v54, v50, v50
	v_max_f32_e32 v50, 0, v55
	v_max_f32_e32 v51, 0, v51
	v_lshl_add_u64 v[60:61], v[120:121], 0, s[30:31]
	v_mul_f32_e32 v52, v52, v52
	v_mul_f32_e32 v49, v49, v49
	v_mul_f32_e32 v50, v50, v50
	v_mul_f32_e32 v51, v51, v51
	v_cvt_pk_bf16_f32 v48, v52, v48
	v_cvt_pk_bf16_f32 v49, v49, v50
	v_cvt_pk_bf16_f32 v50, v56, v53
	v_cvt_pk_bf16_f32 v51, v54, v51
	global_store_dwordx4 v[60:61], v[48:51], off offset:256
	s_mov_b32 s29, 0x240000
	s_mov_b64 s[30:31], 0x240000
	v_mov_b32_e32 v48, v163
	v_pk_mul_f32 v[42:43], v[42:43], v[48:49] op_sel_hi:[1,0]
	v_pk_mul_f32 v[40:41], v[40:41], v[48:49] op_sel_hi:[1,0]
	v_pk_mul_f32 v[46:47], v[46:47], v[48:49] op_sel_hi:[1,0]
	v_pk_mul_f32 v[44:45], v[44:45], v[48:49] op_sel_hi:[1,0]
	v_max_f32_e32 v40, 0, v40
	v_max_f32_e32 v41, 0, v41
	v_max_f32_e32 v42, 0, v42
	v_mul_f32_e32 v49, v40, v40
	v_max_f32_e32 v40, 0, v45
	v_mul_f32_e32 v45, v41, v41
	v_max_f32_e32 v41, 0, v46
	v_mul_f32_e32 v46, v42, v42
	v_max_f32_e32 v42, 0, v47
	v_max_f32_e32 v43, 0, v43
	v_max_f32_e32 v44, 0, v44
	v_mul_f32_e32 v40, v40, v40
	v_mul_f32_e32 v41, v41, v41
	v_mul_f32_e32 v42, v42, v42
	v_mul_f32_e32 v43, v43, v43
	v_mul_f32_e32 v44, v44, v44
	v_cvt_pk_bf16_f32 v40, v44, v40
	v_cvt_pk_bf16_f32 v41, v41, v42
	v_cvt_pk_bf16_f32 v42, v49, v45
	v_cvt_pk_bf16_f32 v43, v46, v43
	v_add_co_u32_e32 v46, vcc, s29, v120
	v_pk_mul_f32 v[22:23], v[22:23], v[48:49] op_sel_hi:[1,0]
	v_pk_mul_f32 v[20:21], v[20:21], v[48:49] op_sel_hi:[1,0]
	v_addc_co_u32_e32 v47, vcc, 0, v121, vcc
	v_pk_mul_f32 v[30:31], v[30:31], v[48:49] op_sel_hi:[1,0]
	v_pk_mul_f32 v[28:29], v[28:29], v[48:49] op_sel_hi:[1,0]
	v_max_f32_e32 v20, 0, v20
	v_max_f32_e32 v21, 0, v21
	v_max_f32_e32 v22, 0, v22
	global_store_dwordx4 v[46:47], v[40:43], off
	v_max_f32_e32 v23, 0, v23
	v_max_f32_e32 v28, 0, v28
	v_mul_f32_e32 v40, v20, v20
	v_max_f32_e32 v20, 0, v29
	v_mul_f32_e32 v29, v21, v21
	v_max_f32_e32 v21, 0, v30
	v_mul_f32_e32 v30, v22, v22
	v_max_f32_e32 v22, 0, v31
	v_mul_f32_e32 v20, v20, v20
	v_mul_f32_e32 v21, v21, v21
	v_mul_f32_e32 v22, v22, v22
	v_mul_f32_e32 v23, v23, v23
	v_lshl_add_u64 v[44:45], v[120:121], 0, s[30:31]
	v_mul_f32_e32 v28, v28, v28
	v_cvt_pk_bf16_f32 v20, v28, v20
	v_cvt_pk_bf16_f32 v21, v21, v22
	v_cvt_pk_bf16_f32 v22, v40, v29
	v_cvt_pk_bf16_f32 v23, v30, v23
	v_pk_mul_f32 v[16:17], v[16:17], v[160:161] op_sel_hi:[1,0]
	global_store_dwordx4 v[44:45], v[20:23], off offset:256
	v_pk_mul_f32 v[18:19], v[18:19], v[160:161] op_sel_hi:[1,0]
	v_max_f32_e32 v16, 0, v16
	v_pk_mul_f32 v[22:23], v[24:25], v[160:161] op_sel_hi:[1,0]
	v_pk_mul_f32 v[20:21], v[26:27], v[160:161] op_sel_hi:[1,0]
	v_max_f32_e32 v22, 0, v22
	v_mul_f32_e32 v24, v16, v16
	v_max_f32_e32 v16, 0, v23
	v_max_f32_e32 v17, 0, v17
	v_max_f32_e32 v18, 0, v18
	v_mul_f32_e32 v22, v22, v22
	v_mul_f32_e32 v16, v16, v16
	v_mul_f32_e32 v23, v17, v17
	v_max_f32_e32 v17, 0, v20
	v_mul_f32_e32 v20, v18, v18
	v_max_f32_e32 v18, 0, v21
	s_mov_b32 s29, 0x280000
	v_mul_f32_e32 v17, v17, v17
	v_max_f32_e32 v19, 0, v19
	v_mul_f32_e32 v18, v18, v18
	v_cvt_pk_bf16_f32 v16, v22, v16
	v_add_co_u32_e32 v22, vcc, s29, v120
	v_mul_f32_e32 v19, v19, v19
	v_cvt_pk_bf16_f32 v17, v17, v18
	v_cvt_pk_bf16_f32 v18, v24, v23
	s_nop 0
	v_addc_co_u32_e32 v23, vcc, 0, v121, vcc
	v_cvt_pk_bf16_f32 v19, v20, v19
	global_store_dwordx4 v[22:23], v[16:19], off
	s_mov_b64 s[30:31], 0x280000
	v_pk_mul_f32 v[22:23], v[38:39], v[160:161] op_sel_hi:[1,0]
	v_pk_mul_f32 v[16:17], v[34:35], v[160:161] op_sel_hi:[1,0]
	v_pk_mul_f32 v[18:19], v[32:33], v[160:161] op_sel_hi:[1,0]
	v_max_f32_e32 v16, 0, v16
	v_pk_mul_f32 v[24:25], v[36:37], v[160:161] op_sel_hi:[1,0]
	v_max_f32_e32 v18, 0, v18
	v_max_f32_e32 v19, 0, v19
	v_mul_f32_e32 v26, v16, v16
	v_max_f32_e32 v16, 0, v17
	v_lshl_add_u64 v[20:21], v[120:121], 0, s[30:31]
	v_max_f32_e32 v24, 0, v24
	v_mul_f32_e32 v18, v18, v18
	v_max_f32_e32 v25, 0, v25
	v_mul_f32_e32 v19, v19, v19
	v_max_f32_e32 v22, 0, v22
	v_max_f32_e32 v17, 0, v23
	v_mul_f32_e32 v23, v16, v16
	v_cvt_pk_bf16_f32 v16, v18, v19
	v_mul_f32_e32 v24, v24, v24
	v_mul_f32_e32 v25, v25, v25
	v_mul_f32_e32 v22, v22, v22
	v_mul_f32_e32 v27, v17, v17
	v_cvt_pk_bf16_f32 v17, v26, v23
	v_cvt_pk_bf16_f32 v18, v24, v25
	v_cvt_pk_bf16_f32 v19, v22, v27
	global_store_dwordx4 v[20:21], v[16:19], off offset:256
	s_mov_b32 s29, 0x2c0000
	s_mov_b64 s[30:31], 0x2c0000
	v_mov_b32_e32 v16, v161
	v_pk_mul_f32 v[0:1], v[0:1], v[16:17] op_sel_hi:[1,0]
	v_pk_mul_f32 v[4:5], v[4:5], v[16:17] op_sel_hi:[1,0]
	v_pk_mul_f32 v[2:3], v[2:3], v[16:17] op_sel_hi:[1,0]
	v_max_f32_e32 v0, 0, v0
	v_pk_mul_f32 v[6:7], v[6:7], v[16:17] op_sel_hi:[1,0]
	v_max_f32_e32 v4, 0, v4
	v_mul_f32_e32 v17, v0, v0
	v_max_f32_e32 v0, 0, v5
	v_max_f32_e32 v1, 0, v1
	v_max_f32_e32 v2, 0, v2
	v_mul_f32_e32 v4, v4, v4
	v_mul_f32_e32 v0, v0, v0
	v_mul_f32_e32 v5, v1, v1
	v_max_f32_e32 v1, 0, v6
	v_mul_f32_e32 v6, v2, v2
	v_max_f32_e32 v2, 0, v7
	v_max_f32_e32 v3, 0, v3
	v_mul_f32_e32 v1, v1, v1
	v_mul_f32_e32 v2, v2, v2
	v_mul_f32_e32 v3, v3, v3
	v_cvt_pk_bf16_f32 v0, v4, v0
	v_add_co_u32_e32 v4, vcc, s29, v120
	v_cvt_pk_bf16_f32 v1, v1, v2
	v_cvt_pk_bf16_f32 v2, v17, v5
	v_cvt_pk_bf16_f32 v3, v6, v3
	v_lshl_add_u64 v[6:7], v[120:121], 0, s[30:31]
	s_nop 0
	v_addc_co_u32_e32 v5, vcc, 0, v121, vcc
	global_store_dwordx4 v[4:5], v[0:3], off
	v_pk_mul_f32 v[4:5], v[14:15], v[16:17] op_sel_hi:[1,0]
	s_nop 0
	v_pk_mul_f32 v[0:1], v[10:11], v[16:17] op_sel_hi:[1,0]
	v_pk_mul_f32 v[2:3], v[8:9], v[16:17] op_sel_hi:[1,0]
	v_pk_mul_f32 v[8:9], v[12:13], v[16:17] op_sel_hi:[1,0]
	v_max_f32_e32 v0, 0, v0
	v_max_f32_e32 v8, 0, v8
	v_mul_f32_e32 v12, v8, v8
	v_max_f32_e32 v8, 0, v9
	v_max_f32_e32 v4, 0, v4
	v_mul_f32_e32 v14, v0, v0
	v_max_f32_e32 v0, 0, v1
	v_max_f32_e32 v1, 0, v5
	v_max_f32_e32 v2, 0, v2
	v_max_f32_e32 v3, 0, v3
	v_mul_f32_e32 v13, v8, v8
	v_mul_f32_e32 v15, v4, v4
	v_mul_f32_e32 v16, v0, v0
	v_mul_f32_e32 v17, v1, v1
	s_waitcnt vmcnt(15)
	v_pk_add_f32 v[0:1], v[138:139], v[142:143]
	v_pk_add_f32 v[4:5], v[136:137], v[140:141]
	v_pk_add_f32 v[8:9], v[130:131], v[134:135]
	v_pk_add_f32 v[10:11], v[128:129], v[132:133]
	v_mul_f32_e32 v2, v2, v2
	v_mul_f32_e32 v3, v3, v3
	v_pk_add_f32 v[0:1], v[0:1], v[8:9]
	v_pk_add_f32 v[4:5], v[4:5], v[10:11]
	v_cvt_pk_bf16_f32 v2, v2, v3
	v_add_f32_e32 v0, v0, v1
	v_add_f32_e32 v3, v4, v5
	v_add_f32_e32 v0, v3, v0
	ds_bpermute_b32 v1, v167, v0
	v_cvt_pk_bf16_f32 v3, v14, v16
	v_cvt_pk_bf16_f32 v4, v12, v13
	v_cvt_pk_bf16_f32 v5, v15, v17
	global_store_dwordx4 v[6:7], v[2:5], off offset:256
	s_and_saveexec_b64 s[38:39], s[34:35]
	s_cbranch_execz .LBB0_1784
	s_waitcnt lgkmcnt(0)
	v_add_f32_e32 v0, v0, v1
	v_fmamk_f32 v0, v0, 0x3a000000, v164
	v_cmp_gt_f32_e32 vcc, s78, v0
	v_mul_f32_e32 v1, 0x4b800000, v0
	s_lshl_b32 s29, s13, 10
	v_cndmask_b32_e32 v0, v0, v1, vcc
	v_rsq_f32_e32 v0, v0
	s_and_b32 s29, s29, 0x400
	v_mul_f32_e32 v1, 0x45800000, v0
	v_cndmask_b32_e32 v0, v0, v1, vcc
	v_add_u32_e32 v1, s29, v170
	ds_write_b32 v1, v0

.LBB0_2200:
	s_waitcnt vmcnt(16)
	v_pk_add_f32 v[0:1], v[118:119], v[114:115]
	v_pk_add_f32 v[2:3], v[116:117], v[112:113]
	v_pk_add_f32 v[4:5], v[108:109], v[104:105]
	v_pk_add_f32 v[6:7], v[110:111], v[106:107]
	v_pk_add_f32 v[2:3], v[2:3], v[4:5]
	v_pk_add_f32 v[0:1], v[0:1], v[6:7]
	v_add_f32_e32 v2, v2, v3
	v_add_f32_e32 v0, v0, v1
	v_add_f32_e32 v0, v2, v0
	ds_bpermute_b32 v1, v194, v0
	s_and_saveexec_b64 s[0:1], s[34:35]
	s_cbranch_execz .LBB0_2202
	s_waitcnt lgkmcnt(0)
	v_add_f32_e32 v0, v0, v1
	v_fmamk_f32 v0, v0, 0x3a000000, v199
	s_mov_b32 s22, 0x800000
	v_cmp_gt_f32_e32 vcc, s22, v0
	v_mul_f32_e32 v1, 0x4b800000, v0
	s_lshl_b32 s22, s82, 10
	v_cndmask_b32_e32 v0, v0, v1, vcc
	v_rsq_f32_e32 v0, v0
	s_and_b32 s22, s22, 0x400
	v_mul_f32_e32 v1, 0x45800000, v0
	v_cndmask_b32_e32 v0, v0, v1, vcc
	v_add_u32_e32 v1, s22, v198
	ds_write_b32 v1, v0

.LBB0_3146:
	s_ashr_i32 s65, s64, 31
	s_lshl_b64 s[38:39], s[64:65], 15
	v_lshl_add_u64 v[140:141], v[158:159], 0, s[38:39]
	global_load_dwordx4 v[128:131], v[140:141], off offset:32
	global_load_dwordx4 v[132:135], v[140:141], off offset:48
	global_load_dwordx4 v[136:139], v[140:141], off
	s_nop 0
	global_load_dwordx4 v[140:143], v[140:141], off offset:16
	v_lshl_or_b32 v176, s29, 8, v172
	s_lshl_b32 s29, s30, 10
	s_and_b32 s29, s29, 0x400
	v_add_u32_e32 v160, s29, v171
	ds_read2_b32 v[178:179], v160 offset1:16
	ds_read2_b32 v[180:181], v160 offset0:32 offset1:48
	ds_read2_b32 v[162:163], v160 offset0:128 offset1:144
	ds_read2_b32 v[160:161], v160 offset0:160 offset1:176
	v_lshl_add_u32 v174, s58, 8, v168
	s_waitcnt lgkmcnt(0)
	v_pk_mul_f32 v[122:123], v[122:123], v[178:179] op_sel_hi:[1,0]
	v_ashrrev_i32_e32 v175, 31, v174
	v_pk_mul_f32 v[126:127], v[126:127], v[178:179] op_sel_hi:[1,0]
	v_pk_mul_f32 v[124:125], v[124:125], v[178:179] op_sel_hi:[1,0]
	v_pk_mul_f32 v[120:121], v[120:121], v[178:179] op_sel_hi:[1,0]
	v_max_f32_e32 v122, 0, v122
	v_lshlrev_b64 v[182:183], 14, v[174:175]
	v_max_f32_e32 v124, 0, v124
	v_max_f32_e32 v120, 0, v120
	v_max_f32_e32 v121, 0, v121
	v_max_f32_e32 v126, 0, v126
	v_mul_f32_e32 v175, v122, v122
	v_max_f32_e32 v122, 0, v127
	v_ashrrev_i32_e32 v177, 31, v176
	v_mul_f32_e32 v124, v124, v124
	v_mul_f32_e32 v120, v120, v120
	v_max_f32_e32 v125, 0, v125
	v_mul_f32_e32 v121, v121, v121
	v_mul_f32_e32 v126, v126, v126
	v_max_f32_e32 v123, 0, v123
	v_mul_f32_e32 v127, v122, v122
	v_mul_f32_e32 v125, v125, v125
	v_mul_f32_e32 v184, v123, v123
	v_cvt_pk_bf16_f32 v122, v124, v125
	v_cvt_pk_bf16_f32 v123, v126, v127
	v_cvt_pk_bf16_f32 v124, v120, v121
	v_lshl_add_u64 v[120:121], s[26:27], 0, v[182:183]
	v_lshlrev_b64 v[126:127], 1, v[176:177]
	v_pk_mul_f32 v[114:115], v[114:115], v[178:179] op_sel_hi:[1,0]
	v_pk_mul_f32 v[112:113], v[112:113], v[178:179] op_sel_hi:[1,0]
	v_lshl_add_u64 v[120:121], v[120:121], 0, v[126:127]
	v_pk_mul_f32 v[118:119], v[118:119], v[178:179] op_sel_hi:[1,0]
	v_pk_mul_f32 v[116:117], v[116:117], v[178:179] op_sel_hi:[1,0]
	v_max_f32_e32 v112, 0, v112
	v_max_f32_e32 v113, 0, v113
	v_max_f32_e32 v114, 0, v114
	v_cvt_pk_bf16_f32 v125, v175, v184
	global_store_dwordx4 v[120:121], v[122:125], off
	v_max_f32_e32 v116, 0, v116
	v_max_f32_e32 v115, 0, v115
	v_mul_f32_e32 v122, v112, v112
	v_max_f32_e32 v112, 0, v117
	v_mul_f32_e32 v117, v113, v113
	v_max_f32_e32 v113, 0, v118
	v_mul_f32_e32 v118, v114, v114
	v_max_f32_e32 v114, 0, v119
	v_mul_f32_e32 v112, v112, v112
	v_mul_f32_e32 v113, v113, v113
	v_mul_f32_e32 v114, v114, v114
	v_mul_f32_e32 v116, v116, v116
	v_mul_f32_e32 v115, v115, v115
	v_cvt_pk_bf16_f32 v112, v116, v112
	v_cvt_pk_bf16_f32 v113, v113, v114
	v_cvt_pk_bf16_f32 v114, v122, v117
	v_cvt_pk_bf16_f32 v115, v118, v115
	global_store_dwordx4 v[120:121], v[112:115], off offset:256
	v_pk_mul_f32 v[90:91], v[90:91], v[180:181] op_sel_hi:[1,0]
	v_pk_mul_f32 v[88:89], v[88:89], v[180:181] op_sel_hi:[1,0]
	v_mov_b32_e32 v114, v179
	v_pk_mul_f32 v[106:107], v[106:107], v[114:115] op_sel_hi:[1,0]
	v_pk_mul_f32 v[104:105], v[104:105], v[114:115] op_sel_hi:[1,0]
	v_or_b32_e32 v112, 16, v174
	v_pk_mul_f32 v[110:111], v[110:111], v[114:115] op_sel_hi:[1,0]
	v_pk_mul_f32 v[108:109], v[108:109], v[114:115] op_sel_hi:[1,0]
	v_max_f32_e32 v104, 0, v104
	v_max_f32_e32 v105, 0, v105
	v_max_f32_e32 v106, 0, v106
	v_ashrrev_i32_e32 v113, 31, v112
	v_max_f32_e32 v108, 0, v108
	v_mul_f32_e32 v115, v104, v104
	v_max_f32_e32 v104, 0, v109
	v_mul_f32_e32 v109, v105, v105
	v_max_f32_e32 v105, 0, v110
	v_mul_f32_e32 v110, v106, v106
	v_max_f32_e32 v106, 0, v111
	v_lshlrev_b64 v[112:113], 14, v[112:113]
	v_mul_f32_e32 v108, v108, v108
	v_mul_f32_e32 v104, v104, v104
	v_mul_f32_e32 v105, v105, v105
	v_mul_f32_e32 v106, v106, v106
	v_max_f32_e32 v107, 0, v107
	v_cvt_pk_bf16_f32 v104, v108, v104
	v_cvt_pk_bf16_f32 v105, v105, v106
	v_cvt_pk_bf16_f32 v106, v115, v109
	v_lshl_add_u64 v[108:109], s[26:27], 0, v[112:113]
	v_pk_mul_f32 v[96:97], v[96:97], v[114:115] op_sel_hi:[1,0]
	v_mul_f32_e32 v107, v107, v107
	v_lshl_add_u64 v[108:109], v[108:109], 0, v[126:127]
	v_pk_mul_f32 v[100:101], v[100:101], v[114:115] op_sel_hi:[1,0]
	v_pk_mul_f32 v[98:99], v[98:99], v[114:115] op_sel_hi:[1,0]
	v_max_f32_e32 v96, 0, v96
	v_cvt_pk_bf16_f32 v107, v110, v107
	global_store_dwordx4 v[108:109], v[104:107], off
	v_pk_mul_f32 v[102:103], v[102:103], v[114:115] op_sel_hi:[1,0]
	v_max_f32_e32 v97, 0, v97
	v_mul_f32_e32 v104, v96, v96
	v_max_f32_e32 v96, 0, v101
	v_max_f32_e32 v98, 0, v98
	v_max_f32_e32 v100, 0, v100
	v_mul_f32_e32 v96, v96, v96
	v_mul_f32_e32 v101, v97, v97
	v_max_f32_e32 v97, 0, v102
	v_mul_f32_e32 v102, v98, v98
	v_max_f32_e32 v98, 0, v103
	v_max_f32_e32 v99, 0, v99
	v_mul_f32_e32 v100, v100, v100
	v_mul_f32_e32 v97, v97, v97
	v_mul_f32_e32 v98, v98, v98
	v_mul_f32_e32 v99, v99, v99
	v_cvt_pk_bf16_f32 v96, v100, v96
	v_cvt_pk_bf16_f32 v97, v97, v98
	v_cvt_pk_bf16_f32 v98, v104, v101
	v_cvt_pk_bf16_f32 v99, v102, v99
	global_store_dwordx4 v[108:109], v[96:99], off offset:256
	v_pk_mul_f32 v[94:95], v[94:95], v[180:181] op_sel_hi:[1,0]
	v_pk_mul_f32 v[92:93], v[92:93], v[180:181] op_sel_hi:[1,0]
	v_or_b32_e32 v96, 32, v174
	v_max_f32_e32 v88, 0, v88
	v_max_f32_e32 v89, 0, v89
	v_max_f32_e32 v90, 0, v90
	v_ashrrev_i32_e32 v97, 31, v96
	v_max_f32_e32 v92, 0, v92
	v_mul_f32_e32 v98, v88, v88
	v_max_f32_e32 v88, 0, v93
	v_mul_f32_e32 v93, v89, v89
	v_max_f32_e32 v89, 0, v94
	v_mul_f32_e32 v94, v90, v90
	v_max_f32_e32 v90, 0, v95
	v_lshlrev_b64 v[96:97], 14, v[96:97]
	v_mul_f32_e32 v92, v92, v92
	v_mul_f32_e32 v88, v88, v88
	v_mul_f32_e32 v89, v89, v89
	v_mul_f32_e32 v90, v90, v90
	v_max_f32_e32 v91, 0, v91
	v_cvt_pk_bf16_f32 v88, v92, v88
	v_cvt_pk_bf16_f32 v89, v89, v90
	v_cvt_pk_bf16_f32 v90, v98, v93
	v_lshl_add_u64 v[92:93], s[26:27], 0, v[96:97]
	v_pk_mul_f32 v[82:83], v[82:83], v[180:181] op_sel_hi:[1,0]
	v_pk_mul_f32 v[80:81], v[80:81], v[180:181] op_sel_hi:[1,0]
	v_mul_f32_e32 v91, v91, v91
	v_lshl_add_u64 v[92:93], v[92:93], 0, v[126:127]
	v_pk_mul_f32 v[86:87], v[86:87], v[180:181] op_sel_hi:[1,0]
	v_pk_mul_f32 v[84:85], v[84:85], v[180:181] op_sel_hi:[1,0]
	v_max_f32_e32 v80, 0, v80
	v_max_f32_e32 v81, 0, v81
	v_max_f32_e32 v82, 0, v82
	v_cvt_pk_bf16_f32 v91, v94, v91
	global_store_dwordx4 v[92:93], v[88:91], off
	v_max_f32_e32 v84, 0, v84
	v_max_f32_e32 v83, 0, v83
	v_mul_f32_e32 v88, v80, v80
	v_max_f32_e32 v80, 0, v85
	v_mul_f32_e32 v85, v81, v81
	v_max_f32_e32 v81, 0, v86
	v_mul_f32_e32 v86, v82, v82
	v_max_f32_e32 v82, 0, v87
	v_mul_f32_e32 v80, v80, v80
	v_mul_f32_e32 v81, v81, v81
	v_mul_f32_e32 v82, v82, v82
	v_mul_f32_e32 v84, v84, v84
	v_mul_f32_e32 v83, v83, v83
	v_cvt_pk_bf16_f32 v80, v84, v80
	v_cvt_pk_bf16_f32 v81, v81, v82
	v_cvt_pk_bf16_f32 v82, v88, v85
	v_cvt_pk_bf16_f32 v83, v86, v83
	global_store_dwordx4 v[92:93], v[80:83], off offset:256
	v_pk_mul_f32 v[58:59], v[58:59], v[162:163] op_sel_hi:[1,0]
	v_pk_mul_f32 v[56:57], v[56:57], v[162:163] op_sel_hi:[1,0]
	v_mov_b32_e32 v82, v181
	v_pk_mul_f32 v[74:75], v[74:75], v[82:83] op_sel_hi:[1,0]
	v_pk_mul_f32 v[72:73], v[72:73], v[82:83] op_sel_hi:[1,0]
	v_or_b32_e32 v80, 48, v174
	v_pk_mul_f32 v[78:79], v[78:79], v[82:83] op_sel_hi:[1,0]
	v_pk_mul_f32 v[76:77], v[76:77], v[82:83] op_sel_hi:[1,0]
	v_max_f32_e32 v72, 0, v72
	v_max_f32_e32 v73, 0, v73
	v_max_f32_e32 v74, 0, v74
	v_ashrrev_i32_e32 v81, 31, v80
	v_max_f32_e32 v76, 0, v76
	v_mul_f32_e32 v83, v72, v72
	v_max_f32_e32 v72, 0, v77
	v_mul_f32_e32 v77, v73, v73
	v_max_f32_e32 v73, 0, v78
	v_mul_f32_e32 v78, v74, v74
	v_max_f32_e32 v74, 0, v79
	v_lshlrev_b64 v[80:81], 14, v[80:81]
	v_mul_f32_e32 v76, v76, v76
	v_mul_f32_e32 v72, v72, v72
	v_mul_f32_e32 v73, v73, v73
	v_mul_f32_e32 v74, v74, v74
	v_max_f32_e32 v75, 0, v75
	v_cvt_pk_bf16_f32 v72, v76, v72
	v_cvt_pk_bf16_f32 v73, v73, v74
	v_cvt_pk_bf16_f32 v74, v83, v77
	v_lshl_add_u64 v[76:77], s[26:27], 0, v[80:81]
	v_pk_mul_f32 v[64:65], v[64:65], v[82:83] op_sel_hi:[1,0]
	v_mul_f32_e32 v75, v75, v75
	v_lshl_add_u64 v[76:77], v[76:77], 0, v[126:127]
	v_pk_mul_f32 v[68:69], v[68:69], v[82:83] op_sel_hi:[1,0]
	v_pk_mul_f32 v[66:67], v[66:67], v[82:83] op_sel_hi:[1,0]
	v_max_f32_e32 v64, 0, v64
	v_cvt_pk_bf16_f32 v75, v78, v75
	global_store_dwordx4 v[76:77], v[72:75], off
	v_pk_mul_f32 v[70:71], v[70:71], v[82:83] op_sel_hi:[1,0]
	v_max_f32_e32 v65, 0, v65
	v_mul_f32_e32 v72, v64, v64
	v_max_f32_e32 v64, 0, v69
	v_max_f32_e32 v66, 0, v66
	v_max_f32_e32 v68, 0, v68
	v_mul_f32_e32 v64, v64, v64
	v_mul_f32_e32 v69, v65, v65
	v_max_f32_e32 v65, 0, v70
	v_mul_f32_e32 v70, v66, v66
	v_max_f32_e32 v66, 0, v71
	v_max_f32_e32 v67, 0, v67
	v_mul_f32_e32 v68, v68, v68
	v_mul_f32_e32 v65, v65, v65
	v_mul_f32_e32 v66, v66, v66
	v_mul_f32_e32 v67, v67, v67
	v_cvt_pk_bf16_f32 v64, v68, v64
	v_pk_mul_f32 v[62:63], v[62:63], v[162:163] op_sel_hi:[1,0]
	v_pk_mul_f32 v[60:61], v[60:61], v[162:163] op_sel_hi:[1,0]
	v_max_f32_e32 v56, 0, v56
	v_max_f32_e32 v57, 0, v57
	v_max_f32_e32 v58, 0, v58
	v_cvt_pk_bf16_f32 v65, v65, v66
	v_cvt_pk_bf16_f32 v66, v72, v69
	v_cvt_pk_bf16_f32 v67, v70, v67
	global_store_dwordx4 v[76:77], v[64:67], off offset:256
	v_max_f32_e32 v59, 0, v59
	v_max_f32_e32 v60, 0, v60
	v_mul_f32_e32 v64, v56, v56
	v_max_f32_e32 v56, 0, v61
	v_mul_f32_e32 v61, v57, v57
	v_max_f32_e32 v57, 0, v62
	v_mul_f32_e32 v62, v58, v58
	v_max_f32_e32 v58, 0, v63
	v_mul_f32_e32 v56, v56, v56
	v_mul_f32_e32 v57, v57, v57
	v_mul_f32_e32 v58, v58, v58
	v_mul_f32_e32 v59, v59, v59
	s_mov_b32 s29, 0x200000
	v_mul_f32_e32 v60, v60, v60
	v_cvt_pk_bf16_f32 v56, v60, v56
	v_cvt_pk_bf16_f32 v57, v57, v58
	v_cvt_pk_bf16_f32 v58, v64, v61
	v_cvt_pk_bf16_f32 v59, v62, v59
	v_add_co_u32_e32 v62, vcc, s29, v120
	v_pk_mul_f32 v[48:49], v[48:49], v[162:163] op_sel_hi:[1,0]
	s_nop 0
	v_addc_co_u32_e32 v63, vcc, 0, v121, vcc
	v_pk_mul_f32 v[52:53], v[52:53], v[162:163] op_sel_hi:[1,0]
	v_pk_mul_f32 v[50:51], v[50:51], v[162:163] op_sel_hi:[1,0]
	v_max_f32_e32 v48, 0, v48
	global_store_dwordx4 v[62:63], v[56:59], off
	v_pk_mul_f32 v[54:55], v[54:55], v[162:163] op_sel_hi:[1,0]
	v_max_f32_e32 v49, 0, v49
	v_mul_f32_e32 v56, v48, v48
	v_max_f32_e32 v48, 0, v53
	v_max_f32_e32 v50, 0, v50
	s_mov_b64 s[30:31], 0x200000
	v_max_f32_e32 v52, 0, v52
	v_mul_f32_e32 v48, v48, v48
	v_mul_f32_e32 v53, v49, v49
	v_max_f32_e32 v49, 0, v54
	v_mul_f32_e32 v54, v50, v50
	v_max_f32_e32 v50, 0, v55
	v_max_f32_e32 v51, 0, v51
	v_lshl_add_u64 v[60:61], v[120:121], 0, s[30:31]
	v_mul_f32_e32 v52, v52, v52
	v_mul_f32_e32 v49, v49, v49
	v_mul_f32_e32 v50, v50, v50
	v_mul_f32_e32 v51, v51, v51
	v_cvt_pk_bf16_f32 v48, v52, v48
	v_cvt_pk_bf16_f32 v49, v49, v50
	v_cvt_pk_bf16_f32 v50, v56, v53
	v_cvt_pk_bf16_f32 v51, v54, v51
	global_store_dwordx4 v[60:61], v[48:51], off offset:256
	s_mov_b32 s29, 0x240000
	s_mov_b64 s[30:31], 0x240000
	v_mov_b32_e32 v48, v163
	v_pk_mul_f32 v[42:43], v[42:43], v[48:49] op_sel_hi:[1,0]
	v_pk_mul_f32 v[40:41], v[40:41], v[48:49] op_sel_hi:[1,0]
	v_pk_mul_f32 v[46:47], v[46:47], v[48:49] op_sel_hi:[1,0]
	v_pk_mul_f32 v[44:45], v[44:45], v[48:49] op_sel_hi:[1,0]
	v_max_f32_e32 v40, 0, v40
	v_max_f32_e32 v41, 0, v41
	v_max_f32_e32 v42, 0, v42
	v_mul_f32_e32 v49, v40, v40
	v_max_f32_e32 v40, 0, v45
	v_mul_f32_e32 v45, v41, v41
	v_max_f32_e32 v41, 0, v46
	v_mul_f32_e32 v46, v42, v42
	v_max_f32_e32 v42, 0, v47
	v_max_f32_e32 v43, 0, v43
	v_max_f32_e32 v44, 0, v44
	v_mul_f32_e32 v40, v40, v40
	v_mul_f32_e32 v41, v41, v41
	v_mul_f32_e32 v42, v42, v42
	v_mul_f32_e32 v43, v43, v43
	v_mul_f32_e32 v44, v44, v44
	v_cvt_pk_bf16_f32 v40, v44, v40
	v_cvt_pk_bf16_f32 v41, v41, v42
	v_cvt_pk_bf16_f32 v42, v49, v45
	v_cvt_pk_bf16_f32 v43, v46, v43
	v_add_co_u32_e32 v46, vcc, s29, v120
	v_pk_mul_f32 v[22:23], v[22:23], v[48:49] op_sel_hi:[1,0]
	v_pk_mul_f32 v[20:21], v[20:21], v[48:49] op_sel_hi:[1,0]
	v_addc_co_u32_e32 v47, vcc, 0, v121, vcc
	v_pk_mul_f32 v[30:31], v[30:31], v[48:49] op_sel_hi:[1,0]
	v_pk_mul_f32 v[28:29], v[28:29], v[48:49] op_sel_hi:[1,0]
	v_max_f32_e32 v20, 0, v20
	v_max_f32_e32 v21, 0, v21
	v_max_f32_e32 v22, 0, v22
	global_store_dwordx4 v[46:47], v[40:43], off
	v_max_f32_e32 v23, 0, v23
	v_max_f32_e32 v28, 0, v28
	v_mul_f32_e32 v40, v20, v20
	v_max_f32_e32 v20, 0, v29
	v_mul_f32_e32 v29, v21, v21
	v_max_f32_e32 v21, 0, v30
	v_mul_f32_e32 v30, v22, v22
	v_max_f32_e32 v22, 0, v31
	v_mul_f32_e32 v20, v20, v20
	v_mul_f32_e32 v21, v21, v21
	v_mul_f32_e32 v22, v22, v22
	v_mul_f32_e32 v23, v23, v23
	v_lshl_add_u64 v[44:45], v[120:121], 0, s[30:31]
	v_mul_f32_e32 v28, v28, v28
	v_cvt_pk_bf16_f32 v20, v28, v20
	v_cvt_pk_bf16_f32 v21, v21, v22
	v_cvt_pk_bf16_f32 v22, v40, v29
	v_cvt_pk_bf16_f32 v23, v30, v23
	v_pk_mul_f32 v[16:17], v[16:17], v[160:161] op_sel_hi:[1,0]
	global_store_dwordx4 v[44:45], v[20:23], off offset:256
	v_pk_mul_f32 v[18:19], v[18:19], v[160:161] op_sel_hi:[1,0]
	v_max_f32_e32 v16, 0, v16
	v_pk_mul_f32 v[22:23], v[24:25], v[160:161] op_sel_hi:[1,0]
	v_pk_mul_f32 v[20:21], v[26:27], v[160:161] op_sel_hi:[1,0]
	v_max_f32_e32 v22, 0, v22
	v_mul_f32_e32 v24, v16, v16
	v_max_f32_e32 v16, 0, v23
	v_max_f32_e32 v17, 0, v17
	v_max_f32_e32 v18, 0, v18
	v_mul_f32_e32 v22, v22, v22
	v_mul_f32_e32 v16, v16, v16
	v_mul_f32_e32 v23, v17, v17
	v_max_f32_e32 v17, 0, v20
	v_mul_f32_e32 v20, v18, v18
	v_max_f32_e32 v18, 0, v21
	s_mov_b32 s29, 0x280000
	v_mul_f32_e32 v17, v17, v17
	v_max_f32_e32 v19, 0, v19
	v_mul_f32_e32 v18, v18, v18
	v_cvt_pk_bf16_f32 v16, v22, v16
	v_add_co_u32_e32 v22, vcc, s29, v120
	v_mul_f32_e32 v19, v19, v19
	v_cvt_pk_bf16_f32 v17, v17, v18
	v_cvt_pk_bf16_f32 v18, v24, v23
	s_nop 0
	v_addc_co_u32_e32 v23, vcc, 0, v121, vcc
	v_cvt_pk_bf16_f32 v19, v20, v19
	global_store_dwordx4 v[22:23], v[16:19], off
	s_mov_b64 s[30:31], 0x280000
	v_pk_mul_f32 v[22:23], v[38:39], v[160:161] op_sel_hi:[1,0]
	v_pk_mul_f32 v[16:17], v[34:35], v[160:161] op_sel_hi:[1,0]
	v_pk_mul_f32 v[18:19], v[32:33], v[160:161] op_sel_hi:[1,0]
	v_max_f32_e32 v16, 0, v16
	v_pk_mul_f32 v[24:25], v[36:37], v[160:161] op_sel_hi:[1,0]
	v_max_f32_e32 v18, 0, v18
	v_max_f32_e32 v19, 0, v19
	v_mul_f32_e32 v26, v16, v16
	v_max_f32_e32 v16, 0, v17
	v_lshl_add_u64 v[20:21], v[120:121], 0, s[30:31]
	v_max_f32_e32 v24, 0, v24
	v_mul_f32_e32 v18, v18, v18
	v_max_f32_e32 v25, 0, v25
	v_mul_f32_e32 v19, v19, v19
	v_max_f32_e32 v22, 0, v22
	v_max_f32_e32 v17, 0, v23
	v_mul_f32_e32 v23, v16, v16
	v_cvt_pk_bf16_f32 v16, v18, v19
	v_mul_f32_e32 v24, v24, v24
	v_mul_f32_e32 v25, v25, v25
	v_mul_f32_e32 v22, v22, v22
	v_mul_f32_e32 v27, v17, v17
	v_cvt_pk_bf16_f32 v17, v26, v23
	v_cvt_pk_bf16_f32 v18, v24, v25
	v_cvt_pk_bf16_f32 v19, v22, v27
	global_store_dwordx4 v[20:21], v[16:19], off offset:256
	s_mov_b32 s29, 0x2c0000
	s_mov_b64 s[30:31], 0x2c0000
	v_mov_b32_e32 v16, v161
	v_pk_mul_f32 v[0:1], v[0:1], v[16:17] op_sel_hi:[1,0]
	v_pk_mul_f32 v[4:5], v[4:5], v[16:17] op_sel_hi:[1,0]
	v_pk_mul_f32 v[2:3], v[2:3], v[16:17] op_sel_hi:[1,0]
	v_max_f32_e32 v0, 0, v0
	v_pk_mul_f32 v[6:7], v[6:7], v[16:17] op_sel_hi:[1,0]
	v_max_f32_e32 v4, 0, v4
	v_mul_f32_e32 v17, v0, v0
	v_max_f32_e32 v0, 0, v5
	v_max_f32_e32 v1, 0, v1
	v_max_f32_e32 v2, 0, v2
	v_mul_f32_e32 v4, v4, v4
	v_mul_f32_e32 v0, v0, v0
	v_mul_f32_e32 v5, v1, v1
	v_max_f32_e32 v1, 0, v6
	v_mul_f32_e32 v6, v2, v2
	v_max_f32_e32 v2, 0, v7
	v_max_f32_e32 v3, 0, v3
	v_mul_f32_e32 v1, v1, v1
	v_mul_f32_e32 v2, v2, v2
	v_mul_f32_e32 v3, v3, v3
	v_cvt_pk_bf16_f32 v0, v4, v0
	v_add_co_u32_e32 v4, vcc, s29, v120
	v_cvt_pk_bf16_f32 v1, v1, v2
	v_cvt_pk_bf16_f32 v2, v17, v5
	v_cvt_pk_bf16_f32 v3, v6, v3
	v_lshl_add_u64 v[6:7], v[120:121], 0, s[30:31]
	s_nop 0
	v_addc_co_u32_e32 v5, vcc, 0, v121, vcc
	global_store_dwordx4 v[4:5], v[0:3], off
	v_pk_mul_f32 v[4:5], v[14:15], v[16:17] op_sel_hi:[1,0]
	s_nop 0
	v_pk_mul_f32 v[0:1], v[10:11], v[16:17] op_sel_hi:[1,0]
	v_pk_mul_f32 v[2:3], v[8:9], v[16:17] op_sel_hi:[1,0]
	v_pk_mul_f32 v[8:9], v[12:13], v[16:17] op_sel_hi:[1,0]
	v_max_f32_e32 v0, 0, v0
	v_max_f32_e32 v8, 0, v8
	v_mul_f32_e32 v12, v8, v8
	v_max_f32_e32 v8, 0, v9
	v_max_f32_e32 v4, 0, v4
	v_mul_f32_e32 v14, v0, v0
	v_max_f32_e32 v0, 0, v1
	v_max_f32_e32 v1, 0, v5
	v_max_f32_e32 v2, 0, v2
	v_max_f32_e32 v3, 0, v3
	v_mul_f32_e32 v13, v8, v8
	v_mul_f32_e32 v15, v4, v4
	v_mul_f32_e32 v16, v0, v0
	v_mul_f32_e32 v17, v1, v1
	s_waitcnt vmcnt(15)
	v_pk_add_f32 v[0:1], v[138:139], v[142:143]
	v_pk_add_f32 v[4:5], v[136:137], v[140:141]
	v_pk_add_f32 v[8:9], v[130:131], v[134:135]
	v_pk_add_f32 v[10:11], v[128:129], v[132:133]
	v_mul_f32_e32 v2, v2, v2
	v_mul_f32_e32 v3, v3, v3
	v_pk_add_f32 v[0:1], v[0:1], v[8:9]
	v_pk_add_f32 v[4:5], v[4:5], v[10:11]
	v_cvt_pk_bf16_f32 v2, v2, v3
	v_add_f32_e32 v0, v0, v1
	v_add_f32_e32 v3, v4, v5
	v_add_f32_e32 v0, v3, v0
	ds_bpermute_b32 v1, v167, v0
	v_cvt_pk_bf16_f32 v3, v14, v16
	v_cvt_pk_bf16_f32 v4, v12, v13
	v_cvt_pk_bf16_f32 v5, v15, v17
	global_store_dwordx4 v[6:7], v[2:5], off offset:256
	s_and_saveexec_b64 s[38:39], s[34:35]
	s_cbranch_execz .LBB0_3148
	s_waitcnt lgkmcnt(0)
	v_add_f32_e32 v0, v0, v1
	v_fmamk_f32 v0, v0, 0x3a000000, v164
	v_cmp_gt_f32_e32 vcc, s75, v0
	v_mul_f32_e32 v1, 0x4b800000, v0
	s_lshl_b32 s29, s13, 10
	v_cndmask_b32_e32 v0, v0, v1, vcc
	v_rsq_f32_e32 v0, v0
	s_and_b32 s29, s29, 0x400
	v_mul_f32_e32 v1, 0x45800000, v0
	v_cndmask_b32_e32 v0, v0, v1, vcc
	v_add_u32_e32 v1, s29, v170
	ds_write_b32 v1, v0

.LBB0_3767:
	s_waitcnt vmcnt(16)
	s_nop 0
	v_pk_add_f32 v[0:1], v[142:143], v[138:139]
	v_pk_add_f32 v[2:3], v[140:141], v[136:137]
	v_pk_add_f32 v[4:5], v[132:133], v[128:129]
	v_pk_add_f32 v[6:7], v[134:135], v[130:131]
	v_pk_add_f32 v[2:3], v[2:3], v[4:5]
	v_pk_add_f32 v[0:1], v[0:1], v[6:7]
	v_add_f32_e32 v2, v2, v3
	v_add_f32_e32 v0, v0, v1
	v_add_f32_e32 v0, v2, v0
	ds_bpermute_b32 v1, v174, v0
	s_and_saveexec_b64 s[38:39], s[34:35]
	s_cbranch_execz .LBB0_3769
	s_waitcnt lgkmcnt(0)
	v_add_f32_e32 v0, v0, v1
	v_fmamk_f32 v0, v0, 0x3a000000, v179
	s_mov_b32 s40, 0x800000
	v_cmp_gt_f32_e32 vcc, s40, v0
	v_mul_f32_e32 v1, 0x4b800000, v0
	s_lshl_b32 s40, s73, 10
	v_cndmask_b32_e32 v0, v0, v1, vcc
	v_rsq_f32_e32 v0, v0
	s_and_b32 s40, s40, 0x400
	v_mul_f32_e32 v1, 0x45800000, v0
	v_cndmask_b32_e32 v0, v0, v1, vcc
	v_add_u32_e32 v1, s40, v178
	ds_write_b32 v1, v0

.LBB0_6483:
	s_waitcnt vmcnt(16)
	v_pk_add_f32 v[10:11], v[14:15], v[10:11]
	v_pk_add_f32 v[8:9], v[12:13], v[8:9]
	v_pk_add_f32 v[0:1], v[4:5], v[0:1]
	v_pk_add_f32 v[2:3], v[6:7], v[2:3]
	v_pk_add_f32 v[0:1], v[8:9], v[0:1]
	v_pk_add_f32 v[2:3], v[10:11], v[2:3]
	v_add_f32_e32 v0, v0, v1
	v_add_f32_e32 v1, v2, v3
	v_add_f32_e32 v0, v0, v1
	ds_bpermute_b32 v1, v198, v0
	s_and_saveexec_b64 s[0:1], s[34:35]
	s_cbranch_execz .LBB0_6485
	s_waitcnt lgkmcnt(0)
	v_add_f32_e32 v0, v0, v1
	v_fmamk_f32 v0, v0, 0x3a000000, v210
	s_mov_b32 s20, 0x800000
	v_cmp_gt_f32_e32 vcc, s20, v0
	v_mul_f32_e32 v1, 0x4b800000, v0
	s_lshl_b32 s20, s94, 10
	v_cndmask_b32_e32 v0, v0, v1, vcc
	v_rsq_f32_e32 v0, v0
	s_and_b32 s20, s20, 0x400
	v_mul_f32_e32 v1, 0x45800000, v0
	v_cndmask_b32_e32 v0, v0, v1, vcc
	v_add_u32_e32 v1, s20, v202
	ds_write_b32 v1, v0

.LBB0_7549:
	s_ashr_i32 s69, s68, 31
	s_lshl_b64 s[38:39], s[68:69], 15
	v_lshl_add_u64 v[140:141], v[158:159], 0, s[38:39]
	s_lshl_b32 s38, s89, 10
	s_and_b32 s38, s38, 0x400
	global_load_dwordx4 v[128:131], v[140:141], off offset:32
	global_load_dwordx4 v[132:135], v[140:141], off offset:48
	global_load_dwordx4 v[136:139], v[140:141], off
	s_nop 0
	global_load_dwordx4 v[140:143], v[140:141], off offset:16
	v_add_u32_e32 v160, s38, v170
	ds_read2_b32 v[178:179], v160 offset1:16
	ds_read2_b32 v[180:181], v160 offset0:32 offset1:48
	ds_read2_b32 v[162:163], v160 offset0:128 offset1:144
	ds_read2_b32 v[160:161], v160 offset0:160 offset1:176
	v_lshl_add_u32 v174, s62, 8, v167
	s_waitcnt lgkmcnt(0)
	v_pk_mul_f32 v[122:123], v[122:123], v[178:179] op_sel_hi:[1,0]
	v_pk_mul_f32 v[126:127], v[126:127], v[178:179] op_sel_hi:[1,0]
	v_pk_mul_f32 v[124:125], v[124:125], v[178:179] op_sel_hi:[1,0]
	v_pk_mul_f32 v[120:121], v[120:121], v[178:179] op_sel_hi:[1,0]
	v_max_f32_e32 v122, 0, v122
	v_lshl_or_b32 v176, s90, 8, v171
	v_ashrrev_i32_e32 v175, 31, v174
	v_max_f32_e32 v124, 0, v124
	v_max_f32_e32 v120, 0, v120
	v_max_f32_e32 v121, 0, v121
	v_max_f32_e32 v126, 0, v126
	v_mul_f32_e32 v173, v122, v122
	v_max_f32_e32 v122, 0, v127
	v_ashrrev_i32_e32 v177, 31, v176
	v_lshlrev_b64 v[182:183], 14, v[174:175]
	v_mul_f32_e32 v124, v124, v124
	v_mul_f32_e32 v120, v120, v120
	v_max_f32_e32 v125, 0, v125
	v_mul_f32_e32 v121, v121, v121
	v_mul_f32_e32 v126, v126, v126
	v_max_f32_e32 v123, 0, v123
	v_mul_f32_e32 v127, v122, v122
	v_mul_f32_e32 v125, v125, v125
	v_mul_f32_e32 v175, v123, v123
	v_cvt_pk_bf16_f32 v122, v124, v125
	v_cvt_pk_bf16_f32 v123, v126, v127
	v_cvt_pk_bf16_f32 v124, v120, v121
	v_lshl_add_u64 v[120:121], s[26:27], 0, v[182:183]
	v_lshlrev_b64 v[126:127], 1, v[176:177]
	v_pk_mul_f32 v[114:115], v[114:115], v[178:179] op_sel_hi:[1,0]
	v_pk_mul_f32 v[112:113], v[112:113], v[178:179] op_sel_hi:[1,0]
	v_lshl_add_u64 v[120:121], v[120:121], 0, v[126:127]
	v_pk_mul_f32 v[118:119], v[118:119], v[178:179] op_sel_hi:[1,0]
	v_pk_mul_f32 v[116:117], v[116:117], v[178:179] op_sel_hi:[1,0]
	v_max_f32_e32 v112, 0, v112
	v_max_f32_e32 v113, 0, v113
	v_max_f32_e32 v114, 0, v114
	v_cvt_pk_bf16_f32 v125, v173, v175
	global_store_dwordx4 v[120:121], v[122:125], off
	v_max_f32_e32 v116, 0, v116
	v_max_f32_e32 v115, 0, v115
	v_mul_f32_e32 v122, v112, v112
	v_max_f32_e32 v112, 0, v117
	v_mul_f32_e32 v117, v113, v113
	v_max_f32_e32 v113, 0, v118
	v_mul_f32_e32 v118, v114, v114
	v_max_f32_e32 v114, 0, v119
	v_mul_f32_e32 v112, v112, v112
	v_mul_f32_e32 v113, v113, v113
	v_mul_f32_e32 v114, v114, v114
	v_mul_f32_e32 v116, v116, v116
	v_mul_f32_e32 v115, v115, v115
	v_cvt_pk_bf16_f32 v112, v116, v112
	v_cvt_pk_bf16_f32 v113, v113, v114
	v_cvt_pk_bf16_f32 v114, v122, v117
	v_cvt_pk_bf16_f32 v115, v118, v115
	global_store_dwordx4 v[120:121], v[112:115], off offset:256
	v_pk_mul_f32 v[90:91], v[90:91], v[180:181] op_sel_hi:[1,0]
	v_pk_mul_f32 v[88:89], v[88:89], v[180:181] op_sel_hi:[1,0]
	v_mov_b32_e32 v114, v179
	v_pk_mul_f32 v[106:107], v[106:107], v[114:115] op_sel_hi:[1,0]
	v_pk_mul_f32 v[104:105], v[104:105], v[114:115] op_sel_hi:[1,0]
	v_or_b32_e32 v112, 16, v174
	v_pk_mul_f32 v[110:111], v[110:111], v[114:115] op_sel_hi:[1,0]
	v_pk_mul_f32 v[108:109], v[108:109], v[114:115] op_sel_hi:[1,0]
	v_max_f32_e32 v104, 0, v104
	v_max_f32_e32 v105, 0, v105
	v_max_f32_e32 v106, 0, v106
	v_ashrrev_i32_e32 v113, 31, v112
	v_max_f32_e32 v108, 0, v108
	v_mul_f32_e32 v115, v104, v104
	v_max_f32_e32 v104, 0, v109
	v_mul_f32_e32 v109, v105, v105
	v_max_f32_e32 v105, 0, v110
	v_mul_f32_e32 v110, v106, v106
	v_max_f32_e32 v106, 0, v111
	v_lshlrev_b64 v[112:113], 14, v[112:113]
	v_mul_f32_e32 v108, v108, v108
	v_mul_f32_e32 v104, v104, v104
	v_mul_f32_e32 v105, v105, v105
	v_mul_f32_e32 v106, v106, v106
	v_max_f32_e32 v107, 0, v107
	v_cvt_pk_bf16_f32 v104, v108, v104
	v_cvt_pk_bf16_f32 v105, v105, v106
	v_cvt_pk_bf16_f32 v106, v115, v109
	v_lshl_add_u64 v[108:109], s[26:27], 0, v[112:113]
	v_pk_mul_f32 v[96:97], v[96:97], v[114:115] op_sel_hi:[1,0]
	v_mul_f32_e32 v107, v107, v107
	v_lshl_add_u64 v[108:109], v[108:109], 0, v[126:127]
	v_pk_mul_f32 v[100:101], v[100:101], v[114:115] op_sel_hi:[1,0]
	v_pk_mul_f32 v[98:99], v[98:99], v[114:115] op_sel_hi:[1,0]
	v_max_f32_e32 v96, 0, v96
	v_cvt_pk_bf16_f32 v107, v110, v107
	global_store_dwordx4 v[108:109], v[104:107], off
	v_pk_mul_f32 v[102:103], v[102:103], v[114:115] op_sel_hi:[1,0]
	v_max_f32_e32 v97, 0, v97
	v_mul_f32_e32 v104, v96, v96
	v_max_f32_e32 v96, 0, v101
	v_max_f32_e32 v98, 0, v98
	v_max_f32_e32 v100, 0, v100
	v_mul_f32_e32 v96, v96, v96
	v_mul_f32_e32 v101, v97, v97
	v_max_f32_e32 v97, 0, v102
	v_mul_f32_e32 v102, v98, v98
	v_max_f32_e32 v98, 0, v103
	v_max_f32_e32 v99, 0, v99
	v_mul_f32_e32 v100, v100, v100
	v_mul_f32_e32 v97, v97, v97
	v_mul_f32_e32 v98, v98, v98
	v_mul_f32_e32 v99, v99, v99
	v_cvt_pk_bf16_f32 v96, v100, v96
	v_cvt_pk_bf16_f32 v97, v97, v98
	v_cvt_pk_bf16_f32 v98, v104, v101
	v_cvt_pk_bf16_f32 v99, v102, v99
	global_store_dwordx4 v[108:109], v[96:99], off offset:256
	v_pk_mul_f32 v[94:95], v[94:95], v[180:181] op_sel_hi:[1,0]
	v_pk_mul_f32 v[92:93], v[92:93], v[180:181] op_sel_hi:[1,0]
	v_or_b32_e32 v96, 32, v174
	v_max_f32_e32 v88, 0, v88
	v_max_f32_e32 v89, 0, v89
	v_max_f32_e32 v90, 0, v90
	v_ashrrev_i32_e32 v97, 31, v96
	v_max_f32_e32 v92, 0, v92
	v_mul_f32_e32 v98, v88, v88
	v_max_f32_e32 v88, 0, v93
	v_mul_f32_e32 v93, v89, v89
	v_max_f32_e32 v89, 0, v94
	v_mul_f32_e32 v94, v90, v90
	v_max_f32_e32 v90, 0, v95
	v_lshlrev_b64 v[96:97], 14, v[96:97]
	v_mul_f32_e32 v92, v92, v92
	v_mul_f32_e32 v88, v88, v88
	v_mul_f32_e32 v89, v89, v89
	v_mul_f32_e32 v90, v90, v90
	v_max_f32_e32 v91, 0, v91
	v_cvt_pk_bf16_f32 v88, v92, v88
	v_cvt_pk_bf16_f32 v89, v89, v90
	v_cvt_pk_bf16_f32 v90, v98, v93
	v_lshl_add_u64 v[92:93], s[26:27], 0, v[96:97]
	v_pk_mul_f32 v[82:83], v[82:83], v[180:181] op_sel_hi:[1,0]
	v_pk_mul_f32 v[80:81], v[80:81], v[180:181] op_sel_hi:[1,0]
	v_mul_f32_e32 v91, v91, v91
	v_lshl_add_u64 v[92:93], v[92:93], 0, v[126:127]
	v_pk_mul_f32 v[86:87], v[86:87], v[180:181] op_sel_hi:[1,0]
	v_pk_mul_f32 v[84:85], v[84:85], v[180:181] op_sel_hi:[1,0]
	v_max_f32_e32 v80, 0, v80
	v_max_f32_e32 v81, 0, v81
	v_max_f32_e32 v82, 0, v82
	v_cvt_pk_bf16_f32 v91, v94, v91
	global_store_dwordx4 v[92:93], v[88:91], off
	v_max_f32_e32 v84, 0, v84
	v_max_f32_e32 v83, 0, v83
	v_mul_f32_e32 v88, v80, v80
	v_max_f32_e32 v80, 0, v85
	v_mul_f32_e32 v85, v81, v81
	v_max_f32_e32 v81, 0, v86
	v_mul_f32_e32 v86, v82, v82
	v_max_f32_e32 v82, 0, v87
	v_mul_f32_e32 v80, v80, v80
	v_mul_f32_e32 v81, v81, v81
	v_mul_f32_e32 v82, v82, v82
	v_mul_f32_e32 v84, v84, v84
	v_mul_f32_e32 v83, v83, v83
	v_cvt_pk_bf16_f32 v80, v84, v80
	v_cvt_pk_bf16_f32 v81, v81, v82
	v_cvt_pk_bf16_f32 v82, v88, v85
	v_cvt_pk_bf16_f32 v83, v86, v83
	global_store_dwordx4 v[92:93], v[80:83], off offset:256
	v_pk_mul_f32 v[58:59], v[58:59], v[162:163] op_sel_hi:[1,0]
	v_pk_mul_f32 v[56:57], v[56:57], v[162:163] op_sel_hi:[1,0]
	v_mov_b32_e32 v82, v181
	v_pk_mul_f32 v[74:75], v[74:75], v[82:83] op_sel_hi:[1,0]
	v_pk_mul_f32 v[72:73], v[72:73], v[82:83] op_sel_hi:[1,0]
	v_or_b32_e32 v80, 48, v174
	v_pk_mul_f32 v[78:79], v[78:79], v[82:83] op_sel_hi:[1,0]
	v_pk_mul_f32 v[76:77], v[76:77], v[82:83] op_sel_hi:[1,0]
	v_max_f32_e32 v72, 0, v72
	v_max_f32_e32 v73, 0, v73
	v_max_f32_e32 v74, 0, v74
	v_ashrrev_i32_e32 v81, 31, v80
	v_max_f32_e32 v76, 0, v76
	v_mul_f32_e32 v83, v72, v72
	v_max_f32_e32 v72, 0, v77
	v_mul_f32_e32 v77, v73, v73
	v_max_f32_e32 v73, 0, v78
	v_mul_f32_e32 v78, v74, v74
	v_max_f32_e32 v74, 0, v79
	v_lshlrev_b64 v[80:81], 14, v[80:81]
	v_mul_f32_e32 v76, v76, v76
	v_mul_f32_e32 v72, v72, v72
	v_mul_f32_e32 v73, v73, v73
	v_mul_f32_e32 v74, v74, v74
	v_max_f32_e32 v75, 0, v75
	v_cvt_pk_bf16_f32 v72, v76, v72
	v_cvt_pk_bf16_f32 v73, v73, v74
	v_cvt_pk_bf16_f32 v74, v83, v77
	v_lshl_add_u64 v[76:77], s[26:27], 0, v[80:81]
	v_pk_mul_f32 v[64:65], v[64:65], v[82:83] op_sel_hi:[1,0]
	v_mul_f32_e32 v75, v75, v75
	v_lshl_add_u64 v[76:77], v[76:77], 0, v[126:127]
	v_pk_mul_f32 v[68:69], v[68:69], v[82:83] op_sel_hi:[1,0]
	v_pk_mul_f32 v[66:67], v[66:67], v[82:83] op_sel_hi:[1,0]
	v_max_f32_e32 v64, 0, v64
	v_cvt_pk_bf16_f32 v75, v78, v75
	global_store_dwordx4 v[76:77], v[72:75], off
	v_pk_mul_f32 v[70:71], v[70:71], v[82:83] op_sel_hi:[1,0]
	v_max_f32_e32 v65, 0, v65
	v_mul_f32_e32 v72, v64, v64
	v_max_f32_e32 v64, 0, v69
	v_max_f32_e32 v66, 0, v66
	v_max_f32_e32 v68, 0, v68
	v_mul_f32_e32 v64, v64, v64
	v_mul_f32_e32 v69, v65, v65
	v_max_f32_e32 v65, 0, v70
	v_mul_f32_e32 v70, v66, v66
	v_max_f32_e32 v66, 0, v71
	v_max_f32_e32 v67, 0, v67
	v_mul_f32_e32 v68, v68, v68
	v_mul_f32_e32 v65, v65, v65
	v_mul_f32_e32 v66, v66, v66
	v_mul_f32_e32 v67, v67, v67
	v_cvt_pk_bf16_f32 v64, v68, v64
	v_pk_mul_f32 v[62:63], v[62:63], v[162:163] op_sel_hi:[1,0]
	v_pk_mul_f32 v[60:61], v[60:61], v[162:163] op_sel_hi:[1,0]
	v_max_f32_e32 v56, 0, v56
	v_max_f32_e32 v57, 0, v57
	v_max_f32_e32 v58, 0, v58
	v_cvt_pk_bf16_f32 v65, v65, v66
	v_cvt_pk_bf16_f32 v66, v72, v69
	v_cvt_pk_bf16_f32 v67, v70, v67
	global_store_dwordx4 v[76:77], v[64:67], off offset:256
	v_max_f32_e32 v60, 0, v60
	v_mul_f32_e32 v60, v60, v60
	v_mul_f32_e32 v64, v56, v56
	v_max_f32_e32 v56, 0, v61
	v_mul_f32_e32 v61, v57, v57
	v_max_f32_e32 v57, 0, v62
	v_mul_f32_e32 v62, v58, v58
	v_max_f32_e32 v58, 0, v63
	v_mul_f32_e32 v56, v56, v56
	v_mul_f32_e32 v57, v57, v57
	v_max_f32_e32 v59, 0, v59
	v_mul_f32_e32 v58, v58, v58
	s_mov_b64 s[38:39], 0x200000
	v_mul_f32_e32 v59, v59, v59
	v_cvt_pk_bf16_f32 v56, v60, v56
	v_cvt_pk_bf16_f32 v57, v57, v58
	v_cvt_pk_bf16_f32 v58, v64, v61
	v_lshl_add_u64 v[60:61], v[120:121], 0, s[38:39]
	s_mov_b32 s38, 0x200000
	v_cvt_pk_bf16_f32 v59, v62, v59
	v_add_co_u32_e32 v62, vcc, s38, v120
	v_pk_mul_f32 v[48:49], v[48:49], v[162:163] op_sel_hi:[1,0]
	s_nop 0
	v_addc_co_u32_e32 v63, vcc, 0, v121, vcc
	v_pk_mul_f32 v[52:53], v[52:53], v[162:163] op_sel_hi:[1,0]
	v_pk_mul_f32 v[50:51], v[50:51], v[162:163] op_sel_hi:[1,0]
	v_max_f32_e32 v48, 0, v48
	global_store_dwordx4 v[62:63], v[56:59], off
	v_pk_mul_f32 v[54:55], v[54:55], v[162:163] op_sel_hi:[1,0]
	v_max_f32_e32 v49, 0, v49
	v_mul_f32_e32 v56, v48, v48
	v_max_f32_e32 v48, 0, v53
	v_max_f32_e32 v50, 0, v50
	v_max_f32_e32 v52, 0, v52
	v_mul_f32_e32 v48, v48, v48
	v_mul_f32_e32 v53, v49, v49
	v_max_f32_e32 v49, 0, v54
	v_mul_f32_e32 v54, v50, v50
	v_max_f32_e32 v50, 0, v55
	v_max_f32_e32 v51, 0, v51
	v_mul_f32_e32 v52, v52, v52
	v_mul_f32_e32 v49, v49, v49
	v_mul_f32_e32 v50, v50, v50
	v_mul_f32_e32 v51, v51, v51
	v_cvt_pk_bf16_f32 v48, v52, v48
	v_cvt_pk_bf16_f32 v49, v49, v50
	v_cvt_pk_bf16_f32 v50, v56, v53
	v_cvt_pk_bf16_f32 v51, v54, v51
	global_store_dwordx4 v[60:61], v[48:51], off offset:256
	s_mov_b64 s[38:39], 0x240000
	v_pk_mul_f32 v[18:19], v[18:19], v[160:161] op_sel_hi:[1,0]
	v_mov_b32_e32 v48, v163
	v_pk_mul_f32 v[42:43], v[42:43], v[48:49] op_sel_hi:[1,0]
	v_pk_mul_f32 v[40:41], v[40:41], v[48:49] op_sel_hi:[1,0]
	v_pk_mul_f32 v[46:47], v[46:47], v[48:49] op_sel_hi:[1,0]
	v_pk_mul_f32 v[44:45], v[44:45], v[48:49] op_sel_hi:[1,0]
	v_max_f32_e32 v40, 0, v40
	v_max_f32_e32 v41, 0, v41
	v_max_f32_e32 v42, 0, v42
	v_max_f32_e32 v44, 0, v44
	v_mul_f32_e32 v49, v40, v40
	v_max_f32_e32 v40, 0, v45
	v_mul_f32_e32 v45, v41, v41
	v_max_f32_e32 v41, 0, v46
	v_mul_f32_e32 v46, v42, v42
	v_max_f32_e32 v42, 0, v47
	v_mul_f32_e32 v44, v44, v44
	v_mul_f32_e32 v40, v40, v40
	v_mul_f32_e32 v41, v41, v41
	v_max_f32_e32 v43, 0, v43
	v_mul_f32_e32 v42, v42, v42
	v_mul_f32_e32 v43, v43, v43
	v_cvt_pk_bf16_f32 v40, v44, v40
	v_cvt_pk_bf16_f32 v41, v41, v42
	v_cvt_pk_bf16_f32 v42, v49, v45
	v_lshl_add_u64 v[44:45], v[120:121], 0, s[38:39]
	s_mov_b32 s38, 0x240000
	v_cvt_pk_bf16_f32 v43, v46, v43
	v_add_co_u32_e32 v46, vcc, s38, v120
	v_pk_mul_f32 v[22:23], v[22:23], v[48:49] op_sel_hi:[1,0]
	v_pk_mul_f32 v[20:21], v[20:21], v[48:49] op_sel_hi:[1,0]
	v_addc_co_u32_e32 v47, vcc, 0, v121, vcc
	v_pk_mul_f32 v[30:31], v[30:31], v[48:49] op_sel_hi:[1,0]
	v_pk_mul_f32 v[28:29], v[28:29], v[48:49] op_sel_hi:[1,0]
	v_max_f32_e32 v20, 0, v20
	v_max_f32_e32 v21, 0, v21
	v_max_f32_e32 v22, 0, v22
	global_store_dwordx4 v[46:47], v[40:43], off
	v_max_f32_e32 v23, 0, v23
	v_max_f32_e32 v28, 0, v28
	v_mul_f32_e32 v40, v20, v20
	v_max_f32_e32 v20, 0, v29
	v_mul_f32_e32 v29, v21, v21
	v_max_f32_e32 v21, 0, v30
	v_mul_f32_e32 v30, v22, v22
	v_max_f32_e32 v22, 0, v31
	v_mul_f32_e32 v20, v20, v20
	v_mul_f32_e32 v21, v21, v21
	v_mul_f32_e32 v22, v22, v22
	v_mul_f32_e32 v23, v23, v23
	v_mul_f32_e32 v28, v28, v28
	v_cvt_pk_bf16_f32 v20, v28, v20
	v_cvt_pk_bf16_f32 v21, v21, v22
	v_cvt_pk_bf16_f32 v22, v40, v29
	v_cvt_pk_bf16_f32 v23, v30, v23
	v_pk_mul_f32 v[16:17], v[16:17], v[160:161] op_sel_hi:[1,0]
	global_store_dwordx4 v[44:45], v[20:23], off offset:256
	v_max_f32_e32 v16, 0, v16
	v_max_f32_e32 v17, 0, v17
	v_pk_mul_f32 v[20:21], v[26:27], v[160:161] op_sel_hi:[1,0]
	v_pk_mul_f32 v[22:23], v[24:25], v[160:161] op_sel_hi:[1,0]
	v_max_f32_e32 v18, 0, v18
	v_mul_f32_e32 v24, v16, v16
	v_max_f32_e32 v16, 0, v23
	v_mul_f32_e32 v23, v17, v17
	v_max_f32_e32 v17, 0, v20
	v_mul_f32_e32 v20, v18, v18
	v_max_f32_e32 v18, 0, v21
	v_max_f32_e32 v19, 0, v19
	v_max_f32_e32 v22, 0, v22
	v_mul_f32_e32 v16, v16, v16
	v_mul_f32_e32 v17, v17, v17
	v_mul_f32_e32 v18, v18, v18
	v_mul_f32_e32 v19, v19, v19
	s_mov_b64 s[38:39], 0x280000
	v_mul_f32_e32 v22, v22, v22
	v_cvt_pk_bf16_f32 v16, v22, v16
	v_cvt_pk_bf16_f32 v17, v17, v18
	v_cvt_pk_bf16_f32 v18, v24, v23
	v_cvt_pk_bf16_f32 v19, v20, v19
	v_lshl_add_u64 v[20:21], v[120:121], 0, s[38:39]
	s_mov_b32 s38, 0x280000
	v_add_co_u32_e32 v22, vcc, s38, v120
	v_pk_mul_f32 v[24:25], v[36:37], v[160:161] op_sel_hi:[1,0]
	s_nop 0
	v_addc_co_u32_e32 v23, vcc, 0, v121, vcc
	global_store_dwordx4 v[22:23], v[16:19], off
	v_pk_mul_f32 v[22:23], v[38:39], v[160:161] op_sel_hi:[1,0]
	v_max_f32_e32 v24, 0, v24
	v_pk_mul_f32 v[16:17], v[34:35], v[160:161] op_sel_hi:[1,0]
	v_pk_mul_f32 v[18:19], v[32:33], v[160:161] op_sel_hi:[1,0]
	v_max_f32_e32 v16, 0, v16
	v_max_f32_e32 v18, 0, v18
	v_max_f32_e32 v19, 0, v19
	v_mul_f32_e32 v26, v16, v16
	v_max_f32_e32 v16, 0, v17
	v_mul_f32_e32 v18, v18, v18
	v_max_f32_e32 v25, 0, v25
	v_mul_f32_e32 v19, v19, v19
	v_max_f32_e32 v22, 0, v22
	v_max_f32_e32 v17, 0, v23
	v_mul_f32_e32 v23, v16, v16
	v_cvt_pk_bf16_f32 v16, v18, v19
	v_mul_f32_e32 v24, v24, v24
	v_mul_f32_e32 v25, v25, v25
	v_mul_f32_e32 v22, v22, v22
	v_mul_f32_e32 v27, v17, v17
	v_cvt_pk_bf16_f32 v17, v26, v23
	v_cvt_pk_bf16_f32 v18, v24, v25
	v_cvt_pk_bf16_f32 v19, v22, v27
	global_store_dwordx4 v[20:21], v[16:19], off offset:256
	s_mov_b64 s[38:39], 0x2c0000
	s_nop 0
	v_mov_b32_e32 v16, v161
	v_pk_mul_f32 v[2:3], v[2:3], v[16:17] op_sel_hi:[1,0]
	v_pk_mul_f32 v[0:1], v[0:1], v[16:17] op_sel_hi:[1,0]
	v_pk_mul_f32 v[6:7], v[6:7], v[16:17] op_sel_hi:[1,0]
	v_pk_mul_f32 v[4:5], v[4:5], v[16:17] op_sel_hi:[1,0]
	v_max_f32_e32 v0, 0, v0
	v_max_f32_e32 v1, 0, v1
	v_max_f32_e32 v2, 0, v2
	v_mul_f32_e32 v17, v0, v0
	v_max_f32_e32 v0, 0, v5
	v_mul_f32_e32 v5, v1, v1
	v_max_f32_e32 v1, 0, v6
	v_mul_f32_e32 v6, v2, v2
	v_max_f32_e32 v2, 0, v7
	v_max_f32_e32 v3, 0, v3
	v_max_f32_e32 v4, 0, v4
	v_mul_f32_e32 v0, v0, v0
	v_mul_f32_e32 v1, v1, v1
	v_mul_f32_e32 v2, v2, v2
	v_mul_f32_e32 v3, v3, v3
	v_mul_f32_e32 v4, v4, v4
	v_cvt_pk_bf16_f32 v0, v4, v0
	v_cvt_pk_bf16_f32 v1, v1, v2
	v_cvt_pk_bf16_f32 v2, v17, v5
	v_cvt_pk_bf16_f32 v3, v6, v3
	v_lshl_add_u64 v[6:7], v[120:121], 0, s[38:39]
	s_mov_b32 s38, 0x2c0000
	v_add_co_u32_e32 v4, vcc, s38, v120
	s_nop 1
	v_addc_co_u32_e32 v5, vcc, 0, v121, vcc
	global_store_dwordx4 v[4:5], v[0:3], off
	v_pk_mul_f32 v[4:5], v[14:15], v[16:17] op_sel_hi:[1,0]
	s_nop 0
	v_pk_mul_f32 v[0:1], v[10:11], v[16:17] op_sel_hi:[1,0]
	v_pk_mul_f32 v[2:3], v[8:9], v[16:17] op_sel_hi:[1,0]
	v_pk_mul_f32 v[8:9], v[12:13], v[16:17] op_sel_hi:[1,0]
	v_max_f32_e32 v0, 0, v0
	v_max_f32_e32 v8, 0, v8
	v_mul_f32_e32 v12, v8, v8
	v_max_f32_e32 v8, 0, v9
	v_max_f32_e32 v4, 0, v4
	v_mul_f32_e32 v14, v0, v0
	v_max_f32_e32 v0, 0, v1
	v_max_f32_e32 v1, 0, v5
	v_max_f32_e32 v2, 0, v2
	v_max_f32_e32 v3, 0, v3
	v_mul_f32_e32 v13, v8, v8
	v_mul_f32_e32 v15, v4, v4
	v_mul_f32_e32 v16, v0, v0
	v_mul_f32_e32 v17, v1, v1
	s_waitcnt vmcnt(15)
	v_pk_add_f32 v[0:1], v[138:139], v[142:143]
	v_pk_add_f32 v[4:5], v[136:137], v[140:141]
	v_pk_add_f32 v[8:9], v[130:131], v[134:135]
	v_pk_add_f32 v[10:11], v[128:129], v[132:133]
	v_mul_f32_e32 v2, v2, v2
	v_mul_f32_e32 v3, v3, v3
	v_pk_add_f32 v[0:1], v[0:1], v[8:9]
	v_pk_add_f32 v[4:5], v[4:5], v[10:11]
	v_cvt_pk_bf16_f32 v2, v2, v3
	v_add_f32_e32 v0, v0, v1
	v_add_f32_e32 v3, v4, v5
	v_add_f32_e32 v0, v3, v0
	ds_bpermute_b32 v1, v166, v0
	v_cvt_pk_bf16_f32 v3, v14, v16
	v_cvt_pk_bf16_f32 v4, v12, v13
	v_cvt_pk_bf16_f32 v5, v15, v17
	global_store_dwordx4 v[6:7], v[2:5], off offset:256
	s_and_saveexec_b64 s[38:39], s[34:35]
	s_cbranch_execz .LBB0_7551
	s_waitcnt lgkmcnt(0)
	v_add_f32_e32 v0, v0, v1
	v_fmamk_f32 v0, v0, 0x3a000000, v164
	v_cmp_gt_f32_e32 vcc, s92, v0
	v_mul_f32_e32 v1, 0x4b800000, v0
	s_lshl_b32 s42, s91, 10
	v_cndmask_b32_e32 v0, v0, v1, vcc
	v_rsq_f32_e32 v0, v0
	s_and_b32 s42, s42, 0x400
	v_mul_f32_e32 v1, 0x45800000, v0
	v_cndmask_b32_e32 v0, v0, v1, vcc
	v_add_u32_e32 v1, s42, v169
	ds_write_b32 v1, v0
